# k6 + workgroups 192..255 do four transpose items before P1
# speedup vs baseline: 1.0195x; 1.0003x over previous
.LBB0_13:
	s_cmpk_gt_i32 s4, 0x21ff
	s_cbranch_scc1 .LBB0_36
	v_lshlrev_b32_e32 v2, 4, v0
	v_and_b32_e32 v26, 0x70, v2
	v_lshlrev_b32_e32 v2, 3, v0
	v_and_b32_e32 v2, 56, v2
	v_mul_u32_u24_e32 v6, 0x84, v2
	v_lshlrev_b32_e32 v2, 1, v2
	v_mov_b32_e32 v3, 0
	s_lshl_b32 s0, s96, 14
	v_lshrrev_b32_e32 v28, 3, v1
	v_lshl_add_u64 v[14:15], s[92:93], 0, v[2:3]
	s_mov_b64 s[8:9], 0x600000
	s_add_i32 s0, s0, 0
	v_lshl_add_u64 v[4:5], v[14:15], 0, s[8:9]
	v_lshlrev_b32_e32 v2, 2, v28
	s_mov_b64 s[8:9], 0xe00000
	v_add3_u32 v36, s0, v6, v2
	v_lshl_add_u64 v[6:7], v[14:15], 0, s[8:9]
	s_mov_b64 s[8:9], 0x2600000
	v_lshl_add_u64 v[8:9], v[14:15], 0, s[8:9]
	s_mov_b64 s[8:9], 0x2200800
	v_add_u32_e32 v37, s0, v26
	v_mul_u32_u24_e32 v38, 0x84, v28
	v_lshl_add_u64 v[10:11], v[14:15], 0, s[8:9]
	s_mov_b64 s[8:9], 0x2200000
	v_lshl_add_u64 v[12:13], v[14:15], 0, s[8:9]
	s_mov_b64 s[8:9], 0x1600000
	v_mov_b32_e32 v27, v3
	s_lshl_b32 s0, s4, 1
	v_add_u32_e32 v37, v37, v38
	s_mov_b32 s1, 0
	v_or_b32_e32 v29, 8, v28
	v_or_b32_e32 v30, 16, v28
	v_or_b32_e32 v31, 24, v28
	v_or_b32_e32 v32, 32, v28
	v_or_b32_e32 v33, 40, v28
	v_or_b32_e32 v34, 48, v28
	v_or_b32_e32 v35, 56, v28
	v_lshl_add_u64 v[14:15], v[14:15], 0, s[8:9]
	v_lshl_add_u64 v[16:17], s[88:89], 0, v[26:27]
	v_lshl_add_u64 v[18:19], s[86:87], 0, v[26:27]
	v_lshl_add_u64 v[20:21], s[84:85], 0, v[26:27]
	s_waitcnt lgkmcnt(0)
	v_lshl_add_u64 v[22:23], s[26:27], 0, v[26:27]
	v_lshl_add_u64 v[24:25], s[24:25], 0, v[26:27]
	v_lshl_add_u64 v[26:27], s[58:59], 0, v[26:27]
	s_lshl_b32 s7, s4, 5
	s_lshl_b32 s10, s6, 5
	s_add_i32 s11, s0, 0x1cc00
	s_lshl_b32 s24, s6, 1
	v_add_u32_e32 v38, 0x420, v37
	v_add_u32_e32 v39, 0x428, v37
	v_add_u32_e32 v40, 0x840, v37
	v_add_u32_e32 v41, 0x848, v37
	v_add_u32_e32 v42, 0xc60, v37
	v_add_u32_e32 v43, 0xc68, v37
	v_add_u32_e32 v44, 0x1080, v37
	v_add_u32_e32 v45, 0x1088, v37
	v_add_u32_e32 v46, 0x14a0, v37
	v_add_u32_e32 v47, 0x14a8, v37
	v_add_u32_e32 v48, 0x18c0, v37
	v_add_u32_e32 v49, 0x18c8, v37
	v_add_u32_e32 v50, 0x1ce0, v37
	v_add_u32_e32 v51, 0x1ce8, v37
	s_movk_i32 s25, 0x6000
	s_mov_b32 s26, s4
	s_cmp_eq_u32 s100, 0
	s_cbranch_scc1 .LBB0_16
	s_mov_b32 s26, s101
	s_cmpk_lt_i32 s26, 0x2000
	s_cbranch_scc1 .Lp0_res_ok
	s_add_i32 s26, s4, 0x1a00
.Lp0_res_ok:
	s_lshl_b32 s7, s26, 5
	s_lshl_b32 s11, s26, 1
	s_add_i32 s11, s11, 0x1cc00
	s_branch .LBB0_16
.LBB0_15:
	s_add_i32 s26, s26, s6
	s_add_i32 s7, s7, s10
	s_add_i32 s11, s11, s24
	s_cmp_lg_u32 s100, 0
	s_cbranch_scc1 .Lp0_pass2
	s_cmpk_lt_i32 s26, 0xc00
	s_cbranch_scc1 .LBB0_16
	s_cmpk_lt_u32 s4, 0x600
	s_cbranch_scc1 .Lp0_p1exit
	s_cmpk_lt_i32 s26, 0x2000
	s_cbranch_scc1 .LBB0_16
